# P0 weight items blocked 2 k-blocks x 4 n-blocks per workgroup (longer contiguous destination rows), on top of v132
# baseline (speedup 1.0000x reference)
; #define SEG_GU(Wsrc, gainp, dst, half) if (r < I_GU) { const int nblk = FF / 64, kb = r / nblk, nb = r % nblk, n0 = 64 * nb; \
;                 p0_item(Wsrc, FF, n0, 64 * kb, gainp, dst, DM, (n0 / 128) * 256 + (n0 % 128) + (half) * 128, scr, lane); continue; } r -= I_GU;
; #define SEG_ID(Wsrc, ldw, colbase, Kdim, ncols, gainp, dst, drow, cnt) if (r < (cnt)) { const int nblk = (ncols) / 64, kb = r / nblk, nb = r % nblk; \
;                 p0_item(Wsrc, ldw, (colbase) + 64 * nb, 64 * kb, gainp, dst, Kdim, (drow) + 64 * nb, scr, lane); continue; } r -= (cnt);
; __global__ void __launch_bounds__(NWAVES * 64, 2) fwd_megakernel(Args args) {
;     ...
;             SEG_GU(args.in[3], args.in[2], W1, 0)
;             SEG_GU(args.in[4], args.in[2], W1, 1)
;             SEG_ID(args.in[5], DM, 0, FF, DM, (const float*)nullptr, WD1, 0, I_DN)
;             SEG_ID(args.in[7], DIN, 0, DM, 1024, args.in[6], WQK, 0, I_IN)
;             SEG_ID(args.in[7], DIN, 1024, DM, 1024, args.in[6], WQK, 1024, I_IN)
;             SEG_ID(args.in[7], DIN, 2048, DM, 1024, args.in[6], WV, 0, I_IN)
;             SEG_ID(args.in[7], DIN, 3080, DM, 1024, args.in[6], WQK, 2048, I_IN)
;             SEG_ID(args.in[7], DIN, 4104, DM, 1024, args.in[6], WQK, 3072, I_IN)
;             SEG_ID(args.in[7], DIN, 5128, DM, 1024, args.in[6], WV, 1024, I_IN)
.Lp0_seg0:
	s_mov_b64 s[28:29], s[14:15]
	s_mov_b64 s[34:35], s[12:13]
	s_add_u32 s36, s60, 0x200000
	s_addc_u32 s37, s61, 0
	s_and_b32 s6, s3, 7
	s_lshr_b32 s7, s3, 3
	s_mul_i32 s4, s7, 0xba3
	s_lshr_b32 s4, s4, 16
	s_mul_i32 s5, s4, 22
	s_sub_u32 s5, s7, s5
	s_lshl_b32 s4, s4, 1
	s_lshr_b32 s7, s6, 2
	s_add_u32 s4, s4, s7
	s_lshl_b32 s5, s5, 2
	s_and_b32 s6, s6, 3
	s_add_u32 s5, s5, s6
	s_lshl_b32 s33, s4, 6
	s_lshl_b32 s31, s5, 6
	s_movk_i32 s30, 0x1600
	s_movk_i32 s38, 0x800
	s_lshr_b32 s6, s5, 1
	s_lshl_b32 s6, s6, 8
	s_and_b32 s7, s5, 1
	s_lshl_b32 s7, s7, 6
	s_add_u32 s39, s6, s7
	s_branch .Lp0_item
.Lp0_seg1:
	s_mov_b64 s[28:29], s[16:17]
	s_mov_b64 s[34:35], s[12:13]
	s_add_u32 s36, s60, 0x200000
	s_addc_u32 s37, s61, 0
	s_and_b32 s6, s3, 7
	s_lshr_b32 s7, s3, 3
	s_mul_i32 s4, s7, 0xba3
	s_lshr_b32 s4, s4, 16
	s_mul_i32 s5, s4, 22
	s_sub_u32 s5, s7, s5
	s_lshl_b32 s4, s4, 1
	s_lshr_b32 s7, s6, 2
	s_add_u32 s4, s4, s7
	s_lshl_b32 s5, s5, 2
	s_and_b32 s6, s6, 3
	s_add_u32 s5, s5, s6
	s_lshl_b32 s33, s4, 6
	s_lshl_b32 s31, s5, 6
	s_movk_i32 s30, 0x1600
	s_movk_i32 s38, 0x800
	s_lshr_b32 s6, s5, 1
	s_lshl_b32 s6, s6, 8
	s_and_b32 s7, s5, 1
	s_lshl_b32 s7, s7, 6
	s_add_u32 s39, s6, s7
	s_add_u32 s39, s39, 0x80
	s_branch .Lp0_item
.Lp0_seg2:
	s_mov_b64 s[28:29], s[18:19]
	s_mov_b64 s[34:35], 0
	s_add_u32 s36, s60, 0x2e00000
	s_addc_u32 s37, s61, 0
	s_and_b32 s6, s3, 7
	s_lshr_b32 s7, s3, 3
	s_lshr_b32 s4, s7, 3
	s_and_b32 s5, s7, 7
	s_lshl_b32 s4, s4, 1
	s_lshr_b32 s7, s6, 2
	s_add_u32 s4, s4, s7
	s_lshl_b32 s5, s5, 2
	s_and_b32 s6, s6, 3
	s_add_u32 s5, s5, s6
	s_lshl_b32 s33, s4, 6
	s_lshl_b32 s5, s5, 6
	s_mov_b32 s31, s5
	s_movk_i32 s30, 0x800
	s_movk_i32 s38, 0x1600
	s_mov_b32 s39, s5
	s_branch .Lp0_item
.Lp0_seg3:
	s_mov_b64 s[28:29], s[22:23]
	s_mov_b64 s[34:35], s[20:21]
	s_add_u32 s36, s60, 0x4400000
	s_addc_u32 s37, s61, 0
	s_and_b32 s6, s3, 7
	s_lshr_b32 s7, s3, 3
	s_lshr_b32 s4, s7, 2
	s_and_b32 s5, s7, 3
	s_lshl_b32 s4, s4, 1
	s_lshr_b32 s7, s6, 2
	s_add_u32 s4, s4, s7
	s_lshl_b32 s5, s5, 2
	s_and_b32 s6, s6, 3
	s_add_u32 s5, s5, s6
	s_lshl_b32 s33, s4, 6
	s_lshl_b32 s5, s5, 6
	s_mov_b32 s31, s5
	s_movk_i32 s30, 0x1808
	s_movk_i32 s38, 0x800
	s_mov_b32 s39, s5
	s_branch .Lp0_item
.Lp0_seg4:
	s_mov_b64 s[28:29], s[22:23]
	s_mov_b64 s[34:35], s[20:21]
	s_add_u32 s36, s60, 0x4400000
	s_addc_u32 s37, s61, 0
	s_and_b32 s6, s3, 7
	s_lshr_b32 s7, s3, 3
	s_lshr_b32 s4, s7, 2
	s_and_b32 s5, s7, 3
	s_lshl_b32 s4, s4, 1
	s_lshr_b32 s7, s6, 2
	s_add_u32 s4, s4, s7
	s_lshl_b32 s5, s5, 2
	s_and_b32 s6, s6, 3
	s_add_u32 s5, s5, s6
	s_lshl_b32 s33, s4, 6
	s_lshl_b32 s5, s5, 6
	s_add_u32 s31, s5, 0x400
	s_movk_i32 s30, 0x1808
	s_movk_i32 s38, 0x800
	s_add_u32 s39, s5, 0x400
	s_branch .Lp0_item
.Lp0_seg5:
	s_mov_b64 s[28:29], s[22:23]
	s_mov_b64 s[34:35], s[20:21]
	s_add_u32 s36, s60, 0x5400000
	s_addc_u32 s37, s61, 0
	s_and_b32 s6, s3, 7
	s_lshr_b32 s7, s3, 3
	s_lshr_b32 s4, s7, 2
	s_and_b32 s5, s7, 3
	s_lshl_b32 s4, s4, 1
	s_lshr_b32 s7, s6, 2
	s_add_u32 s4, s4, s7
	s_lshl_b32 s5, s5, 2
	s_and_b32 s6, s6, 3
	s_add_u32 s5, s5, s6
	s_lshl_b32 s33, s4, 6
	s_lshl_b32 s5, s5, 6
	s_add_u32 s31, s5, 0x800
	s_movk_i32 s30, 0x1808
	s_movk_i32 s38, 0x800
	s_mov_b32 s39, s5
	s_branch .Lp0_item
.Lp0_seg6:
	s_mov_b64 s[28:29], s[22:23]
	s_mov_b64 s[34:35], s[20:21]
	s_add_u32 s36, s60, 0x4400000
	s_addc_u32 s37, s61, 0
	s_and_b32 s6, s3, 7
	s_lshr_b32 s7, s3, 3
	s_lshr_b32 s4, s7, 2
	s_and_b32 s5, s7, 3
	s_lshl_b32 s4, s4, 1
	s_lshr_b32 s7, s6, 2
	s_add_u32 s4, s4, s7
	s_lshl_b32 s5, s5, 2
	s_and_b32 s6, s6, 3
	s_add_u32 s5, s5, s6
	s_lshl_b32 s33, s4, 6
	s_lshl_b32 s5, s5, 6
	s_add_u32 s31, s5, 0xc08
	s_movk_i32 s30, 0x1808
	s_movk_i32 s38, 0x800
	s_add_u32 s39, s5, 0x800
	s_branch .Lp0_item
.Lp0_seg7:
	s_mov_b64 s[28:29], s[22:23]
	s_mov_b64 s[34:35], s[20:21]
	s_add_u32 s36, s60, 0x4400000
	s_addc_u32 s37, s61, 0
	s_and_b32 s6, s3, 7
	s_lshr_b32 s7, s3, 3
	s_lshr_b32 s4, s7, 2
	s_and_b32 s5, s7, 3
	s_lshl_b32 s4, s4, 1
	s_lshr_b32 s7, s6, 2
	s_add_u32 s4, s4, s7
	s_lshl_b32 s5, s5, 2
	s_and_b32 s6, s6, 3
	s_add_u32 s5, s5, s6
	s_lshl_b32 s33, s4, 6
	s_lshl_b32 s5, s5, 6
	s_add_u32 s31, s5, 0x1008
	s_movk_i32 s30, 0x1808
	s_movk_i32 s38, 0x800
	s_add_u32 s39, s5, 0xc00
	s_branch .Lp0_item
; #define SEG_GU(Wsrc, gainp, dst, half) if (r < I_GU) { const int nblk = FF / 64, kb = r / nblk, nb = r % nblk, n0 = 64 * nb; \
;                 p0_item(Wsrc, FF, n0, 64 * kb, gainp, dst, DM, (n0 / 128) * 256 + (n0 % 128) + (half) * 128, scr, lane); continue; } r -= I_GU;
; #define SEG_ID(Wsrc, ldw, colbase, Kdim, ncols, gainp, dst, drow, cnt) if (r < (cnt)) { const int nblk = (ncols) / 64, kb = r / nblk, nb = r % nblk; \
;                 p0_item(Wsrc, ldw, (colbase) + 64 * nb, 64 * kb, gainp, dst, Kdim, (drow) + 64 * nb, scr, lane); continue; } r -= (cnt);
; __global__ void __launch_bounds__(NWAVES * 64, 2) fwd_megakernel(Args args) {
;     ...
;             SEG_ID(args.in[7], DIN, 3080, DM, 1024, args.in[6], WQK, 2048, I_IN)
;             SEG_ID(args.in[7], DIN, 4104, DM, 1024, args.in[6], WQK, 3072, I_IN)
;             SEG_ID(args.in[7], DIN, 5128, DM, 1024, args.in[6], WV, 1024, I_IN)
;             SEG_ID(args.in[9], DM, 0, DM, DM, (const float*)nullptr, WO, 0, I_SQ)
;             SEG_GU(args.in[11], args.in[10], W2, 0)
;             SEG_GU(args.in[12], args.in[10], W2, 1)
;             SEG_ID(args.in[13], DM, 0, FF, DM, (const float*)nullptr, WD2, 0, I_DN)
;             SEG_ID(args.in[15], DM, 0, DM, DM, args.in[14], WPG, 0, I_SQ)
;             SEG_ID(args.in[16], DM, 0, PLE, DM, (const float*)nullptr, WPP, 0, I_PP)
.Lp0_seg8:
	s_mov_b64 s[28:29], s[22:23]
	s_mov_b64 s[34:35], s[20:21]
	s_add_u32 s36, s60, 0x5400000
	s_addc_u32 s37, s61, 0
	s_and_b32 s6, s3, 7
	s_lshr_b32 s7, s3, 3
	s_lshr_b32 s4, s7, 2
	s_and_b32 s5, s7, 3
	s_lshl_b32 s4, s4, 1
	s_lshr_b32 s7, s6, 2
	s_add_u32 s4, s4, s7
	s_lshl_b32 s5, s5, 2
	s_and_b32 s6, s6, 3
	s_add_u32 s5, s5, s6
	s_lshl_b32 s33, s4, 6
	s_lshl_b32 s5, s5, 6
	s_add_u32 s31, s5, 0x1408
	s_movk_i32 s30, 0x1808
	s_movk_i32 s38, 0x800
	s_add_u32 s39, s5, 0x400
	s_branch .Lp0_item
.Lp0_seg9:
	v_readlane_b32 s28, v250, 14
	v_readlane_b32 s29, v250, 15
	s_mov_b64 s[34:35], 0
	s_add_u32 s36, s60, 0x5c00000
	s_addc_u32 s37, s61, 0
	s_and_b32 s6, s3, 7
	s_lshr_b32 s7, s3, 3
	s_lshr_b32 s4, s7, 3
	s_and_b32 s5, s7, 7
	s_lshl_b32 s4, s4, 1
	s_lshr_b32 s7, s6, 2
	s_add_u32 s4, s4, s7
	s_lshl_b32 s5, s5, 2
	s_and_b32 s6, s6, 3
	s_add_u32 s5, s5, s6
	s_lshl_b32 s33, s4, 6
	s_lshl_b32 s5, s5, 6
	s_mov_b32 s31, s5
	s_movk_i32 s30, 0x800
	s_movk_i32 s38, 0x800
	s_mov_b32 s39, s5
	s_branch .Lp0_item
.Lp0_seg10:
	v_readlane_b32 s28, v250, 18
	v_readlane_b32 s29, v250, 19
	v_readlane_b32 s34, v250, 16
	v_readlane_b32 s35, v250, 17
	s_add_u32 s36, s60, 0x6400000
	s_addc_u32 s37, s61, 0
	s_and_b32 s6, s3, 7
	s_lshr_b32 s7, s3, 3
	s_mul_i32 s4, s7, 0xba3
	s_lshr_b32 s4, s4, 16
	s_mul_i32 s5, s4, 22
	s_sub_u32 s5, s7, s5
	s_lshl_b32 s4, s4, 1
	s_lshr_b32 s7, s6, 2
	s_add_u32 s4, s4, s7
	s_lshl_b32 s5, s5, 2
	s_and_b32 s6, s6, 3
	s_add_u32 s5, s5, s6
	s_lshl_b32 s33, s4, 6
	s_lshl_b32 s31, s5, 6
	s_movk_i32 s30, 0x1600
	s_movk_i32 s38, 0x800
	s_lshr_b32 s6, s5, 1
	s_lshl_b32 s6, s6, 8
	s_and_b32 s7, s5, 1
	s_lshl_b32 s7, s7, 6
	s_add_u32 s39, s6, s7
	s_branch .Lp0_item
.Lp0_seg11:
	v_readlane_b32 s28, v250, 20
	v_readlane_b32 s29, v250, 21
	v_readlane_b32 s34, v250, 16
	v_readlane_b32 s35, v250, 17
	s_add_u32 s36, s60, 0x6400000
	s_addc_u32 s37, s61, 0
	s_and_b32 s6, s3, 7
	s_lshr_b32 s7, s3, 3
	s_mul_i32 s4, s7, 0xba3
	s_lshr_b32 s4, s4, 16
	s_mul_i32 s5, s4, 22
	s_sub_u32 s5, s7, s5
	s_lshl_b32 s4, s4, 1
	s_lshr_b32 s7, s6, 2
	s_add_u32 s4, s4, s7
	s_lshl_b32 s5, s5, 2
	s_and_b32 s6, s6, 3
	s_add_u32 s5, s5, s6
	s_lshl_b32 s33, s4, 6
	s_lshl_b32 s31, s5, 6
	s_movk_i32 s30, 0x1600
	s_movk_i32 s38, 0x800
	s_lshr_b32 s6, s5, 1
	s_lshl_b32 s6, s6, 8
	s_and_b32 s7, s5, 1
	s_lshl_b32 s7, s7, 6
	s_add_u32 s39, s6, s7
	s_add_u32 s39, s39, 0x80
	s_branch .Lp0_item
.Lp0_seg12:
	v_readlane_b32 s28, v250, 22
	v_readlane_b32 s29, v250, 23
	s_mov_b64 s[34:35], 0
	s_add_u32 s36, s60, 0x9000000
	s_addc_u32 s37, s61, 0
	s_and_b32 s6, s3, 7
	s_lshr_b32 s7, s3, 3
	s_lshr_b32 s4, s7, 3
	s_and_b32 s5, s7, 7
	s_lshl_b32 s4, s4, 1
	s_lshr_b32 s7, s6, 2
	s_add_u32 s4, s4, s7
	s_lshl_b32 s5, s5, 2
	s_and_b32 s6, s6, 3
	s_add_u32 s5, s5, s6
	s_lshl_b32 s33, s4, 6
	s_lshl_b32 s5, s5, 6
	s_mov_b32 s31, s5
	s_movk_i32 s30, 0x800
	s_movk_i32 s38, 0x1600
	s_mov_b32 s39, s5
	s_branch .Lp0_item
.Lp0_seg13:
	v_readlane_b32 s28, v250, 26
	v_readlane_b32 s29, v250, 27
	v_readlane_b32 s34, v250, 24
	v_readlane_b32 s35, v250, 25
	s_add_u32 s36, s60, 0xa600000
	s_addc_u32 s37, s61, 0
	s_and_b32 s6, s3, 7
	s_lshr_b32 s7, s3, 3
	s_lshr_b32 s4, s7, 3
	s_and_b32 s5, s7, 7
	s_lshl_b32 s4, s4, 1
	s_lshr_b32 s7, s6, 2
	s_add_u32 s4, s4, s7
	s_lshl_b32 s5, s5, 2
	s_and_b32 s6, s6, 3
	s_add_u32 s5, s5, s6
	s_lshl_b32 s33, s4, 6
	s_lshl_b32 s5, s5, 6
	s_mov_b32 s31, s5
	s_movk_i32 s30, 0x800
	s_movk_i32 s38, 0x800
	s_mov_b32 s39, s5
	s_branch .Lp0_item
.Lp0_seg14:
	v_readlane_b32 s28, v250, 0
	v_readlane_b32 s29, v250, 1
	s_mov_b64 s[34:35], 0
	s_add_u32 s36, s60, 0xae00000
	s_addc_u32 s37, s61, 0
	s_and_b32 s6, s3, 7
	s_lshr_b32 s7, s3, 3
	s_lshr_b32 s4, s7, 3
	s_and_b32 s5, s7, 7
	s_lshl_b32 s4, s4, 1
	s_lshr_b32 s7, s6, 2
	s_add_u32 s4, s4, s7
	s_lshl_b32 s5, s5, 2
	s_and_b32 s6, s6, 3
	s_add_u32 s5, s5, s6
	s_lshl_b32 s33, s4, 6
	s_lshl_b32 s5, s5, 6
	s_mov_b32 s31, s5
	s_movk_i32 s30, 0x800
	s_movk_i32 s38, 0x100
	s_mov_b32 s39, s5
	s_branch .Lp0_item
